# v48 + proj (rope tiles) epilogue: the two 16-byte stores of a lane become two full-128B-line stores via row_ror:8 exchange
# baseline (speedup 1.0000x reference)
; __device__ __forceinline__ u32x4 pack8(const f32x4 a, const f32x4 b) { u32x4 w; w.x = cvt_pk_bf16(a[0], a[1]); w.y = cvt_pk_bf16(a[2], a[3]); w.z = cvt_pk_bf16(b[0], b[1]); w.w = cvt_pk_bf16(b[2], b[3]); return w; }
;     __device__ __forceinline__ void operator()(const f32x4 (&acc)[2][2][4][2], const pg8::Unit& u, int wr, int wc, int fr, int fq) const {
;     ...
;                 bf16_t* pr = P + (size_t)row * NP_ + u.pn * 256;
;                 if (rope) { f32x4 o1[2], o2[2];
; #pragma unroll
;                     for (int n = 0; n < 2; ++n) { const f32x4 c = cv[mm][n], s = sv[mm][n];
;                         o1[n] = t1[n] * c - t2[n] * s; o2[n] = t2[n] * c + t1[n] * s; }
;                     if (qsc) { o1[0] *= SC2_; o1[1] *= SC2_; o2[0] *= SC2_; o2[1] *= SC2_; }
;                     *(u32x4*)(pr + wc * 64 + fq * 8) = pack8(o1[0], o1[1]); *(u32x4*)(pr + wc * 64 + 32 + fq * 8) = pack8(o2[0], o2[1]);
.LBB0_468:
	s_mov_b32 s3, s1
	s_lshl_b32 s2, s53, 1
	v_lshl_add_u64 v[156:157], v[156:157], 0, s[2:3]
	v_lshlrev_b32_e32 v0, 1, v170
	v_cvt_pk_bf16_f32 v152, v224, v225
	v_cvt_pk_bf16_f32 v153, v222, v223
	v_cvt_pk_bf16_f32 v154, v220, v221
	v_cvt_pk_bf16_f32 v155, v218, v219
	v_lshl_add_u64 v[156:157], v[156:157], 0, v[0:1]
	v_cvt_pk_bf16_f32 v218, v160, v161
	v_cvt_pk_bf16_f32 v219, v158, v159
	v_cvt_pk_bf16_f32 v220, v150, v151
	v_cvt_pk_bf16_f32 v221, v148, v149
	v_mov_b32_e32 v222, v152
	v_mov_b32_e32 v223, v153
	v_mov_b32_e32 v224, v154
	v_mov_b32_e32 v225, v155
	v_bfe_u32 v148, v227, 3, 1
	v_mul_i32_i24_e32 v148, 0xffff2040, v148
	v_ashrrev_i32_e32 v149, 31, v148
	v_lshl_add_u64 v[148:149], v[156:157], 0, v[148:149]
	v_mov_b32_e32 v150, 0xe000
	v_mov_b32_e32 v151, 0
	v_lshl_add_u64 v[150:151], v[148:149], 0, v[150:151]
	v_mov_b32_dpp v152, v218 row_ror:8 row_mask:0xf bank_mask:0xc
	v_mov_b32_dpp v153, v219 row_ror:8 row_mask:0xf bank_mask:0xc
	v_mov_b32_dpp v154, v220 row_ror:8 row_mask:0xf bank_mask:0xc
	v_mov_b32_dpp v155, v221 row_ror:8 row_mask:0xf bank_mask:0xc
	v_mov_b32_dpp v218, v222 row_ror:8 row_mask:0xf bank_mask:0x3
	v_mov_b32_dpp v219, v223 row_ror:8 row_mask:0xf bank_mask:0x3
	v_mov_b32_dpp v220, v224 row_ror:8 row_mask:0xf bank_mask:0x3
	v_mov_b32_dpp v221, v225 row_ror:8 row_mask:0xf bank_mask:0x3
	global_store_dwordx4 v[148:149], v[152:155], off
	global_store_dwordx4 v[150:151], v[218:221], off
	s_nop 1

; __device__ __forceinline__ u32x4 pack8(const f32x4 a, const f32x4 b) { u32x4 w; w.x = cvt_pk_bf16(a[0], a[1]); w.y = cvt_pk_bf16(a[2], a[3]); w.z = cvt_pk_bf16(b[0], b[1]); w.w = cvt_pk_bf16(b[2], b[3]); return w; }
;     __device__ __forceinline__ void operator()(const f32x4 (&acc)[2][2][4][2], const pg8::Unit& u, int wr, int wc, int fr, int fq) const {
;     ...
;                 bf16_t* pr = P + (size_t)row * NP_ + u.pn * 256;
;                 if (rope) { f32x4 o1[2], o2[2];
; #pragma unroll
;                     for (int n = 0; n < 2; ++n) { const f32x4 c = cv[mm][n], s = sv[mm][n];
;                         o1[n] = t1[n] * c - t2[n] * s; o2[n] = t2[n] * c + t1[n] * s; }
;                     if (qsc) { o1[0] *= SC2_; o1[1] *= SC2_; o2[0] *= SC2_; o2[1] *= SC2_; }
;                     *(u32x4*)(pr + wc * 64 + fq * 8) = pack8(o1[0], o1[1]); *(u32x4*)(pr + wc * 64 + 32 + fq * 8) = pack8(o2[0], o2[1]);
.LBB0_474:
	s_mov_b32 s3, s1
	s_lshl_b32 s2, s53, 1
	v_lshl_add_u64 v[138:139], v[138:139], 0, s[2:3]
	v_lshlrev_b32_e32 v0, 1, v170
	v_cvt_pk_bf16_f32 v134, v154, v155
	v_cvt_pk_bf16_f32 v135, v152, v153
	v_cvt_pk_bf16_f32 v136, v148, v149
	v_cvt_pk_bf16_f32 v137, v144, v145
	v_lshl_add_u64 v[138:139], v[138:139], 0, v[0:1]
	v_cvt_pk_bf16_f32 v152, v142, v143
	v_cvt_pk_bf16_f32 v153, v140, v141
	v_cvt_pk_bf16_f32 v154, v132, v133
	v_cvt_pk_bf16_f32 v155, v130, v131
	v_mov_b32_e32 v144, v134
	v_mov_b32_e32 v145, v135
	v_mov_b32_e32 v148, v136
	v_mov_b32_e32 v149, v137
	v_bfe_u32 v130, v227, 3, 1
	v_mul_i32_i24_e32 v130, 0xffff2040, v130
	v_ashrrev_i32_e32 v131, 31, v130
	v_lshl_add_u64 v[130:131], v[138:139], 0, v[130:131]
	v_mov_b32_e32 v132, 0xe000
	v_mov_b32_e32 v133, 0
	v_lshl_add_u64 v[132:133], v[130:131], 0, v[132:133]
	v_mov_b32_dpp v134, v152 row_ror:8 row_mask:0xf bank_mask:0xc
	v_mov_b32_dpp v135, v153 row_ror:8 row_mask:0xf bank_mask:0xc
	v_mov_b32_dpp v136, v154 row_ror:8 row_mask:0xf bank_mask:0xc
	v_mov_b32_dpp v137, v155 row_ror:8 row_mask:0xf bank_mask:0xc
	v_mov_b32_dpp v152, v144 row_ror:8 row_mask:0xf bank_mask:0x3
	v_mov_b32_dpp v153, v145 row_ror:8 row_mask:0xf bank_mask:0x3
	v_mov_b32_dpp v154, v148 row_ror:8 row_mask:0xf bank_mask:0x3
	v_mov_b32_dpp v155, v149 row_ror:8 row_mask:0xf bank_mask:0x3
	global_store_dwordx4 v[130:131], v[134:137], off
	global_store_dwordx4 v[132:133], v[152:155], off
	s_nop 1

; __device__ __forceinline__ u32x4 pack8(const f32x4 a, const f32x4 b) { u32x4 w; w.x = cvt_pk_bf16(a[0], a[1]); w.y = cvt_pk_bf16(a[2], a[3]); w.z = cvt_pk_bf16(b[0], b[1]); w.w = cvt_pk_bf16(b[2], b[3]); return w; }
;     __device__ __forceinline__ void operator()(const f32x4 (&acc)[2][2][4][2], const pg8::Unit& u, int wr, int wc, int fr, int fq) const {
;     ...
;                 bf16_t* pr = P + (size_t)row * NP_ + u.pn * 256;
;                 if (rope) { f32x4 o1[2], o2[2];
; #pragma unroll
;                     for (int n = 0; n < 2; ++n) { const f32x4 c = cv[mm][n], s = sv[mm][n];
;                         o1[n] = t1[n] * c - t2[n] * s; o2[n] = t2[n] * c + t1[n] * s; }
;                     if (qsc) { o1[0] *= SC2_; o1[1] *= SC2_; o2[0] *= SC2_; o2[1] *= SC2_; }
;                     *(u32x4*)(pr + wc * 64 + fq * 8) = pack8(o1[0], o1[1]); *(u32x4*)(pr + wc * 64 + 32 + fq * 8) = pack8(o2[0], o2[1]);
.LBB0_482:
	s_mov_b32 s3, s1
	s_lshl_b32 s2, s53, 1
	v_lshl_add_u64 v[122:123], v[122:123], 0, s[2:3]
	v_lshlrev_b32_e32 v0, 1, v170
	v_cvt_pk_bf16_f32 v118, v136, v137
	v_cvt_pk_bf16_f32 v119, v134, v135
	v_cvt_pk_bf16_f32 v120, v130, v131
	v_cvt_pk_bf16_f32 v121, v128, v129
	v_lshl_add_u64 v[122:123], v[122:123], 0, v[0:1]
	v_cvt_pk_bf16_f32 v128, v126, v127
	v_cvt_pk_bf16_f32 v129, v124, v125
	v_cvt_pk_bf16_f32 v130, v116, v117
	v_cvt_pk_bf16_f32 v131, v114, v115
	v_mov_b32_e32 v134, v118
	v_mov_b32_e32 v135, v119
	v_mov_b32_e32 v136, v120
	v_mov_b32_e32 v137, v121
	v_bfe_u32 v114, v227, 3, 1
	v_mul_i32_i24_e32 v114, 0xffff2040, v114
	v_ashrrev_i32_e32 v115, 31, v114
	v_lshl_add_u64 v[114:115], v[122:123], 0, v[114:115]
	v_mov_b32_e32 v116, 0xe000
	v_mov_b32_e32 v117, 0
	v_lshl_add_u64 v[116:117], v[114:115], 0, v[116:117]
	v_mov_b32_dpp v118, v128 row_ror:8 row_mask:0xf bank_mask:0xc
	v_mov_b32_dpp v119, v129 row_ror:8 row_mask:0xf bank_mask:0xc
	v_mov_b32_dpp v120, v130 row_ror:8 row_mask:0xf bank_mask:0xc
	v_mov_b32_dpp v121, v131 row_ror:8 row_mask:0xf bank_mask:0xc
	v_mov_b32_dpp v128, v134 row_ror:8 row_mask:0xf bank_mask:0x3
	v_mov_b32_dpp v129, v135 row_ror:8 row_mask:0xf bank_mask:0x3
	v_mov_b32_dpp v130, v136 row_ror:8 row_mask:0xf bank_mask:0x3
	v_mov_b32_dpp v131, v137 row_ror:8 row_mask:0xf bank_mask:0x3
	global_store_dwordx4 v[114:115], v[118:121], off
	global_store_dwordx4 v[116:117], v[128:131], off
	s_nop 1

; __device__ __forceinline__ u32x4 pack8(const f32x4 a, const f32x4 b) { u32x4 w; w.x = cvt_pk_bf16(a[0], a[1]); w.y = cvt_pk_bf16(a[2], a[3]); w.z = cvt_pk_bf16(b[0], b[1]); w.w = cvt_pk_bf16(b[2], b[3]); return w; }
;     __device__ __forceinline__ void operator()(const f32x4 (&acc)[2][2][4][2], const pg8::Unit& u, int wr, int wc, int fr, int fq) const {
;     ...
;                 bf16_t* pr = P + (size_t)row * NP_ + u.pn * 256;
;                 if (rope) { f32x4 o1[2], o2[2];
; #pragma unroll
;                     for (int n = 0; n < 2; ++n) { const f32x4 c = cv[mm][n], s = sv[mm][n];
;                         o1[n] = t1[n] * c - t2[n] * s; o2[n] = t2[n] * c + t1[n] * s; }
;                     if (qsc) { o1[0] *= SC2_; o1[1] *= SC2_; o2[0] *= SC2_; o2[1] *= SC2_; }
;                     *(u32x4*)(pr + wc * 64 + fq * 8) = pack8(o1[0], o1[1]); *(u32x4*)(pr + wc * 64 + 32 + fq * 8) = pack8(o2[0], o2[1]);
.LBB0_488:
	s_mov_b32 s3, s1
	s_lshl_b32 s2, s53, 1
	v_lshl_add_u64 v[106:107], v[106:107], 0, s[2:3]
	v_lshlrev_b32_e32 v0, 1, v170
	v_cvt_pk_bf16_f32 v102, v120, v121
	v_cvt_pk_bf16_f32 v103, v118, v119
	v_cvt_pk_bf16_f32 v104, v114, v115
	v_cvt_pk_bf16_f32 v105, v112, v113
	v_lshl_add_u64 v[106:107], v[106:107], 0, v[0:1]
	v_cvt_pk_bf16_f32 v112, v110, v111
	v_cvt_pk_bf16_f32 v113, v108, v109
	v_cvt_pk_bf16_f32 v114, v100, v101
	v_cvt_pk_bf16_f32 v115, v98, v99
	v_mov_b32_e32 v118, v102
	v_mov_b32_e32 v119, v103
	v_mov_b32_e32 v120, v104
	v_mov_b32_e32 v121, v105
	v_bfe_u32 v98, v227, 3, 1
	v_mul_i32_i24_e32 v98, 0xffff2040, v98
	v_ashrrev_i32_e32 v99, 31, v98
	v_lshl_add_u64 v[98:99], v[106:107], 0, v[98:99]
	v_mov_b32_e32 v100, 0xe000
	v_mov_b32_e32 v101, 0
	v_lshl_add_u64 v[100:101], v[98:99], 0, v[100:101]
	v_mov_b32_dpp v102, v112 row_ror:8 row_mask:0xf bank_mask:0xc
	v_mov_b32_dpp v103, v113 row_ror:8 row_mask:0xf bank_mask:0xc
	v_mov_b32_dpp v104, v114 row_ror:8 row_mask:0xf bank_mask:0xc
	v_mov_b32_dpp v105, v115 row_ror:8 row_mask:0xf bank_mask:0xc
	v_mov_b32_dpp v112, v118 row_ror:8 row_mask:0xf bank_mask:0x3
	v_mov_b32_dpp v113, v119 row_ror:8 row_mask:0xf bank_mask:0x3
	v_mov_b32_dpp v114, v120 row_ror:8 row_mask:0xf bank_mask:0x3
	v_mov_b32_dpp v115, v121 row_ror:8 row_mask:0xf bank_mask:0x3
	global_store_dwordx4 v[98:99], v[102:105], off
	global_store_dwordx4 v[100:101], v[112:115], off
	s_nop 1

; __device__ __forceinline__ u32x4 pack8(const f32x4 a, const f32x4 b) { u32x4 w; w.x = cvt_pk_bf16(a[0], a[1]); w.y = cvt_pk_bf16(a[2], a[3]); w.z = cvt_pk_bf16(b[0], b[1]); w.w = cvt_pk_bf16(b[2], b[3]); return w; }
;     __device__ __forceinline__ void operator()(const f32x4 (&acc)[2][2][4][2], const pg8::Unit& u, int wr, int wc, int fr, int fq) const {
;     ...
;                 bf16_t* pr = P + (size_t)row * NP_ + u.pn * 256;
;                 if (rope) { f32x4 o1[2], o2[2];
; #pragma unroll
;                     for (int n = 0; n < 2; ++n) { const f32x4 c = cv[mm][n], s = sv[mm][n];
;                         o1[n] = t1[n] * c - t2[n] * s; o2[n] = t2[n] * c + t1[n] * s; }
;                     if (qsc) { o1[0] *= SC2_; o1[1] *= SC2_; o2[0] *= SC2_; o2[1] *= SC2_; }
;                     *(u32x4*)(pr + wc * 64 + fq * 8) = pack8(o1[0], o1[1]); *(u32x4*)(pr + wc * 64 + 32 + fq * 8) = pack8(o2[0], o2[1]);
.LBB0_496:
	s_mov_b32 s3, s1
	s_lshl_b32 s2, s53, 1
	v_lshl_add_u64 v[90:91], v[90:91], 0, s[2:3]
	v_lshlrev_b32_e32 v0, 1, v170
	v_cvt_pk_bf16_f32 v86, v122, v123
	v_cvt_pk_bf16_f32 v87, v116, v117
	v_cvt_pk_bf16_f32 v88, v118, v119
	v_cvt_pk_bf16_f32 v89, v96, v97
	v_lshl_add_u64 v[90:91], v[90:91], 0, v[0:1]
	v_cvt_pk_bf16_f32 v116, v94, v95
	v_cvt_pk_bf16_f32 v117, v92, v93
	v_cvt_pk_bf16_f32 v118, v84, v85
	v_cvt_pk_bf16_f32 v119, v82, v83
	v_mov_b32_e32 v96, v86
	v_mov_b32_e32 v97, v87
	v_mov_b32_e32 v122, v88
	v_mov_b32_e32 v123, v89
	v_bfe_u32 v82, v227, 3, 1
	v_mul_i32_i24_e32 v82, 0xffff2040, v82
	v_ashrrev_i32_e32 v83, 31, v82
	v_lshl_add_u64 v[82:83], v[90:91], 0, v[82:83]
	v_mov_b32_e32 v84, 0xe000
	v_mov_b32_e32 v85, 0
	v_lshl_add_u64 v[84:85], v[82:83], 0, v[84:85]
	v_mov_b32_dpp v86, v116 row_ror:8 row_mask:0xf bank_mask:0xc
	v_mov_b32_dpp v87, v117 row_ror:8 row_mask:0xf bank_mask:0xc
	v_mov_b32_dpp v88, v118 row_ror:8 row_mask:0xf bank_mask:0xc
	v_mov_b32_dpp v89, v119 row_ror:8 row_mask:0xf bank_mask:0xc
	v_mov_b32_dpp v116, v96 row_ror:8 row_mask:0xf bank_mask:0x3
	v_mov_b32_dpp v117, v97 row_ror:8 row_mask:0xf bank_mask:0x3
	v_mov_b32_dpp v118, v122 row_ror:8 row_mask:0xf bank_mask:0x3
	v_mov_b32_dpp v119, v123 row_ror:8 row_mask:0xf bank_mask:0x3
	global_store_dwordx4 v[82:83], v[86:89], off
	global_store_dwordx4 v[84:85], v[116:119], off
	s_nop 1

; __device__ __forceinline__ u32x4 pack8(const f32x4 a, const f32x4 b) { u32x4 w; w.x = cvt_pk_bf16(a[0], a[1]); w.y = cvt_pk_bf16(a[2], a[3]); w.z = cvt_pk_bf16(b[0], b[1]); w.w = cvt_pk_bf16(b[2], b[3]); return w; }
;     __device__ __forceinline__ void operator()(const f32x4 (&acc)[2][2][4][2], const pg8::Unit& u, int wr, int wc, int fr, int fq) const {
;     ...
;                 bf16_t* pr = P + (size_t)row * NP_ + u.pn * 256;
;                 if (rope) { f32x4 o1[2], o2[2];
; #pragma unroll
;                     for (int n = 0; n < 2; ++n) { const f32x4 c = cv[mm][n], s = sv[mm][n];
;                         o1[n] = t1[n] * c - t2[n] * s; o2[n] = t2[n] * c + t1[n] * s; }
;                     if (qsc) { o1[0] *= SC2_; o1[1] *= SC2_; o2[0] *= SC2_; o2[1] *= SC2_; }
;                     *(u32x4*)(pr + wc * 64 + fq * 8) = pack8(o1[0], o1[1]); *(u32x4*)(pr + wc * 64 + 32 + fq * 8) = pack8(o2[0], o2[1]);
.LBB0_502:
	s_mov_b32 s3, s1
	s_lshl_b32 s2, s53, 1
	v_lshl_add_u64 v[58:59], v[58:59], 0, s[2:3]
	v_lshlrev_b32_e32 v0, 1, v170
	v_cvt_pk_bf16_f32 v54, v88, v89
	v_cvt_pk_bf16_f32 v55, v86, v87
	v_cvt_pk_bf16_f32 v56, v82, v83
	v_cvt_pk_bf16_f32 v57, v64, v65
	v_lshl_add_u64 v[58:59], v[58:59], 0, v[0:1]
	v_cvt_pk_bf16_f32 v86, v62, v63
	v_cvt_pk_bf16_f32 v87, v60, v61
	v_cvt_pk_bf16_f32 v88, v52, v53
	v_cvt_pk_bf16_f32 v89, v50, v51
	v_mov_b32_e32 v64, v54
	v_mov_b32_e32 v65, v55
	v_mov_b32_e32 v82, v56
	v_mov_b32_e32 v83, v57
	v_bfe_u32 v50, v227, 3, 1
	v_mul_i32_i24_e32 v50, 0xffff2040, v50
	v_ashrrev_i32_e32 v51, 31, v50
	v_lshl_add_u64 v[50:51], v[58:59], 0, v[50:51]
	v_mov_b32_e32 v52, 0xe000
	v_mov_b32_e32 v53, 0
	v_lshl_add_u64 v[52:53], v[50:51], 0, v[52:53]
	v_mov_b32_dpp v54, v86 row_ror:8 row_mask:0xf bank_mask:0xc
	v_mov_b32_dpp v55, v87 row_ror:8 row_mask:0xf bank_mask:0xc
	v_mov_b32_dpp v56, v88 row_ror:8 row_mask:0xf bank_mask:0xc
	v_mov_b32_dpp v57, v89 row_ror:8 row_mask:0xf bank_mask:0xc
	v_mov_b32_dpp v86, v64 row_ror:8 row_mask:0xf bank_mask:0x3
	v_mov_b32_dpp v87, v65 row_ror:8 row_mask:0xf bank_mask:0x3
	v_mov_b32_dpp v88, v82 row_ror:8 row_mask:0xf bank_mask:0x3
	v_mov_b32_dpp v89, v83 row_ror:8 row_mask:0xf bank_mask:0x3
	global_store_dwordx4 v[50:51], v[54:57], off
	global_store_dwordx4 v[52:53], v[86:89], off
	s_nop 1

; __device__ __forceinline__ u32x4 pack8(const f32x4 a, const f32x4 b) { u32x4 w; w.x = cvt_pk_bf16(a[0], a[1]); w.y = cvt_pk_bf16(a[2], a[3]); w.z = cvt_pk_bf16(b[0], b[1]); w.w = cvt_pk_bf16(b[2], b[3]); return w; }
;     __device__ __forceinline__ void operator()(const f32x4 (&acc)[2][2][4][2], const pg8::Unit& u, int wr, int wc, int fr, int fq) const {
;     ...
;                 bf16_t* pr = P + (size_t)row * NP_ + u.pn * 256;
;                 if (rope) { f32x4 o1[2], o2[2];
; #pragma unroll
;                     for (int n = 0; n < 2; ++n) { const f32x4 c = cv[mm][n], s = sv[mm][n];
;                         o1[n] = t1[n] * c - t2[n] * s; o2[n] = t2[n] * c + t1[n] * s; }
;                     if (qsc) { o1[0] *= SC2_; o1[1] *= SC2_; o2[0] *= SC2_; o2[1] *= SC2_; }
;                     *(u32x4*)(pr + wc * 64 + fq * 8) = pack8(o1[0], o1[1]); *(u32x4*)(pr + wc * 64 + 32 + fq * 8) = pack8(o2[0], o2[1]);
.LBB0_510:
	s_mov_b32 s3, s1
	s_lshl_b32 s2, s53, 1
	v_lshl_add_u64 v[26:27], v[26:27], 0, s[2:3]
	v_lshlrev_b32_e32 v0, 1, v170
	v_cvt_pk_bf16_f32 v22, v56, v57
	v_cvt_pk_bf16_f32 v23, v54, v55
	v_cvt_pk_bf16_f32 v24, v50, v51
	v_cvt_pk_bf16_f32 v25, v32, v33
	v_lshl_add_u64 v[26:27], v[26:27], 0, v[0:1]
	v_cvt_pk_bf16_f32 v54, v30, v31
	v_cvt_pk_bf16_f32 v55, v28, v29
	v_cvt_pk_bf16_f32 v56, v20, v21
	v_cvt_pk_bf16_f32 v57, v18, v19
	v_mov_b32_e32 v32, v22
	v_mov_b32_e32 v33, v23
	v_mov_b32_e32 v50, v24
	v_mov_b32_e32 v51, v25
	v_bfe_u32 v18, v227, 3, 1
	v_mul_i32_i24_e32 v18, 0xffff2040, v18
	v_ashrrev_i32_e32 v19, 31, v18
	v_lshl_add_u64 v[18:19], v[26:27], 0, v[18:19]
	v_mov_b32_e32 v20, 0xe000
	v_mov_b32_e32 v21, 0
	v_lshl_add_u64 v[20:21], v[18:19], 0, v[20:21]
	v_mov_b32_dpp v22, v54 row_ror:8 row_mask:0xf bank_mask:0xc
	v_mov_b32_dpp v23, v55 row_ror:8 row_mask:0xf bank_mask:0xc
	v_mov_b32_dpp v24, v56 row_ror:8 row_mask:0xf bank_mask:0xc
	v_mov_b32_dpp v25, v57 row_ror:8 row_mask:0xf bank_mask:0xc
	v_mov_b32_dpp v54, v32 row_ror:8 row_mask:0xf bank_mask:0x3
	v_mov_b32_dpp v55, v33 row_ror:8 row_mask:0xf bank_mask:0x3
	v_mov_b32_dpp v56, v50 row_ror:8 row_mask:0xf bank_mask:0x3
	v_mov_b32_dpp v57, v51 row_ror:8 row_mask:0xf bank_mask:0x3
	global_store_dwordx4 v[18:19], v[22:25], off
	global_store_dwordx4 v[20:21], v[54:57], off
	s_nop 1

; __device__ __forceinline__ u32x4 pack8(const f32x4 a, const f32x4 b) { u32x4 w; w.x = cvt_pk_bf16(a[0], a[1]); w.y = cvt_pk_bf16(a[2], a[3]); w.z = cvt_pk_bf16(b[0], b[1]); w.w = cvt_pk_bf16(b[2], b[3]); return w; }
;     __device__ __forceinline__ void operator()(const f32x4 (&acc)[2][2][4][2], const pg8::Unit& u, int wr, int wc, int fr, int fq) const {
;     ...
;                 bf16_t* pr = P + (size_t)row * NP_ + u.pn * 256;
;                 if (rope) { f32x4 o1[2], o2[2];
; #pragma unroll
;                     for (int n = 0; n < 2; ++n) { const f32x4 c = cv[mm][n], s = sv[mm][n];
;                         o1[n] = t1[n] * c - t2[n] * s; o2[n] = t2[n] * c + t1[n] * s; }
;                     if (qsc) { o1[0] *= SC2_; o1[1] *= SC2_; o2[0] *= SC2_; o2[1] *= SC2_; }
;                     *(u32x4*)(pr + wc * 64 + fq * 8) = pack8(o1[0], o1[1]); *(u32x4*)(pr + wc * 64 + 32 + fq * 8) = pack8(o2[0], o2[1]);
.LBB0_516:
	s_mov_b32 s3, s1
	s_lshl_b32 s2, s53, 1
	v_lshl_add_u64 v[10:11], v[10:11], 0, s[2:3]
	v_lshlrev_b32_e32 v0, 1, v170
	v_cvt_pk_bf16_f32 v6, v24, v25
	v_cvt_pk_bf16_f32 v7, v22, v23
	v_cvt_pk_bf16_f32 v8, v18, v19
	v_cvt_pk_bf16_f32 v9, v16, v17
	v_lshl_add_u64 v[10:11], v[10:11], 0, v[0:1]
	v_cvt_pk_bf16_f32 v16, v14, v15
	v_cvt_pk_bf16_f32 v17, v12, v13
	v_cvt_pk_bf16_f32 v18, v4, v5
	v_cvt_pk_bf16_f32 v19, v2, v3
	v_mov_b32_e32 v22, v6
	v_mov_b32_e32 v23, v7
	v_mov_b32_e32 v24, v8
	v_mov_b32_e32 v25, v9
	v_bfe_u32 v2, v227, 3, 1
	v_mul_i32_i24_e32 v2, 0xffff2040, v2
	v_ashrrev_i32_e32 v3, 31, v2
	v_lshl_add_u64 v[2:3], v[10:11], 0, v[2:3]
	v_mov_b32_e32 v4, 0xe000
	v_mov_b32_e32 v5, 0
	v_lshl_add_u64 v[4:5], v[2:3], 0, v[4:5]
	v_mov_b32_dpp v6, v16 row_ror:8 row_mask:0xf bank_mask:0xc
	v_mov_b32_dpp v7, v17 row_ror:8 row_mask:0xf bank_mask:0xc
	v_mov_b32_dpp v8, v18 row_ror:8 row_mask:0xf bank_mask:0xc
	v_mov_b32_dpp v9, v19 row_ror:8 row_mask:0xf bank_mask:0xc
	v_mov_b32_dpp v16, v22 row_ror:8 row_mask:0xf bank_mask:0x3
	v_mov_b32_dpp v17, v23 row_ror:8 row_mask:0xf bank_mask:0x3
	v_mov_b32_dpp v18, v24 row_ror:8 row_mask:0xf bank_mask:0x3
	v_mov_b32_dpp v19, v25 row_ror:8 row_mask:0xf bank_mask:0x3
	global_store_dwordx4 v[2:3], v[6:9], off
	global_store_dwordx4 v[4:5], v[16:19], off
	s_nop 1
